# P3/P10: the last unit's trailing (unused) K-tile re-loads point at the tile pair just consumed (L2-hot) instead of K-tiles 0/1, on top of v129
# speedup vs baseline: 1.0003x; 1.0003x over previous
.LBB0_233:
	v_cndmask_b32_e64 v2, 0, 1, s[4:5]
	v_cmp_ne_u32_e64 s[0:1], 1, v2
	s_andn2_b64 vcc, exec, s[4:5]
	s_add_u32 s28, s18, 0x1500
	s_addc_u32 s29, s19, 0
	s_cbranch_vccnz .LBB0_235
	s_mul_i32 s9, s93, 0x160000
	s_mul_hi_i32 s8, s93, 0x160000
	s_add_u32 s28, s74, s9
	s_addc_u32 s29, s75, s8
.LBB0_235:
	s_and_b64 vcc, exec, s[0:1]
	s_add_u32 s0, s14, 0x1500
	s_addc_u32 s1, s15, 0
	s_cbranch_vccnz .LBB0_237
	s_mul_i32 s0, s92, 0x160000
	s_mul_hi_i32 s1, s92, 0x160000
	s_add_u32 s0, s76, s0
	s_addc_u32 s1, s77, s1

.LBB0_703:
	v_cndmask_b32_e64 v138, 0, 1, s[6:7]
	v_cmp_ne_u32_e64 s[4:5], 1, v138
	s_andn2_b64 vcc, exec, s[6:7]
	s_add_u32 s6, s14, 0xa00
	s_addc_u32 s7, s15, 0
	s_cbranch_vccnz .LBB0_705
	s_mul_i32 s6, s50, 0xb0000
	s_mul_hi_i32 s7, s50, 0xb0000
	s_add_u32 s6, s30, s6
	s_addc_u32 s7, s31, s7
.LBB0_705:
	s_and_b64 vcc, exec, s[4:5]
	s_add_u32 s16, s0, 0xa00
	s_addc_u32 s17, s1, 0
	s_cbranch_vccnz .LBB0_707
	s_mul_i32 s9, s49, 0xb0000
	s_mul_hi_i32 s8, s49, 0xb0000
	s_add_u32 s16, s36, s9
	s_addc_u32 s17, s37, s8
